# v14 + in-proj epilogue: 24-bit row*ld products instead of 64-bit multiplies
# speedup vs baseline: 1.0214x; 1.0023x over previous
; __device__ __forceinline__ unsigned pk2(float lo, float hi) { v2f v = {lo, hi}; return __builtin_bit_cast(unsigned, __builtin_convertvector(v, v2bf)); }
;     __device__ __forceinline__ void operator()(const f32x4 (&acc)[2][2][4][2], const Unit& u, int wr, int wc, int fr, int fq) const {
;         const int row0 = u.pm * 256 + wr * 64 + fr; int col0 = u.pn * 256 + wc * 32 + 8 * fq; int ld = ldz; bf16* base = Z;
;         if (SEG) { int c0, w; seg_of(u.pn * 256, c0, w); base = Z + (size_t)T * c0; ld = w; col0 -= c0; }
; #pragma unroll
;         for (int ai = 0; ai < 2; ++ai)
; #pragma unroll
;             for (int m = 0; m < 4; ++m) { bf16* rowp = base + (size_t)(row0 + ai * 128 + m * 16) * ld + col0;
; #pragma unroll
;                 for (int bj = 0; bj < 2; ++bj) { const f32x4 v0 = acc[ai][bj][m][0], v1 = acc[ai][bj][m][1];
;                     v4u w; w.x = pk2(v0[0], v0[1]); w.y = pk2(v0[2], v0[3]); w.z = pk2(v1[0], v1[1]); w.w = pk2(v1[2], v1[3]);
;                     *(v4u*)(rowp + bj * 128) = w; } }
.LBB0_84:
	s_ashr_i32 s41, s40, 31
	v_lshl_add_u32 v148, s78, 8, v140
	s_lshl_b64 s[50:51], s[40:41], 15
	v_or_b32_e32 v144, s7, v142
	s_add_u32 s50, s46, s50
	v_subrev_u32_e32 v144, s40, v144
	s_addc_u32 s51, s47, s51
	v_ashrrev_i32_e32 v145, 31, v144
	v_mul_u32_u24_e32 v146, s10, v148
	v_mov_b32_e32 v147, 0
	v_cvt_pk_bf16_f32 v110, v110, v111
	v_cvt_pk_bf16_f32 v111, v112, v113
	v_cvt_pk_bf16_f32 v112, v106, v107
	v_or_b32_e32 v106, 16, v148
	v_lshl_add_u64 v[144:145], v[144:145], 1, s[50:51]
	v_cvt_pk_bf16_f32 v113, v108, v109
	v_mul_u32_u24_e32 v106, s10, v106
	v_mov_b32_e32 v107, 0
	v_cvt_pk_bf16_f32 v94, v94, v95
	v_cvt_pk_bf16_f32 v95, v96, v97
	v_cvt_pk_bf16_f32 v96, v90, v91
	v_or_b32_e32 v90, 32, v148
	v_cvt_pk_bf16_f32 v70, v70, v71
	v_cvt_pk_bf16_f32 v71, v72, v73
	v_cvt_pk_bf16_f32 v72, v66, v67
	v_add_u32_e32 v66, 0x80, v148
	v_lshl_add_u64 v[146:147], v[146:147], 1, v[144:145]
	v_cvt_pk_bf16_f32 v97, v92, v93
	v_mul_u32_u24_e32 v90, s10, v90
	v_mov_b32_e32 v91, 0
	v_cvt_pk_bf16_f32 v78, v78, v79
	v_cvt_pk_bf16_f32 v79, v80, v81
	v_cvt_pk_bf16_f32 v80, v74, v75
	v_or_b32_e32 v74, 48, v148
	v_cvt_pk_bf16_f32 v46, v46, v47
	v_cvt_pk_bf16_f32 v47, v48, v49
	v_cvt_pk_bf16_f32 v48, v42, v43
	v_add_u32_e32 v42, 0x90, v148
	v_cvt_pk_bf16_f32 v126, v126, v127
	v_cvt_pk_bf16_f32 v127, v128, v129
	v_cvt_pk_bf16_f32 v128, v122, v123
	v_cvt_pk_bf16_f32 v129, v124, v125
	global_store_dwordx4 v[146:147], v[110:113], off offset:256
	s_nop 1
	v_cvt_pk_bf16_f32 v81, v76, v77
	v_lshl_add_u64 v[110:111], v[106:107], 1, v[144:145]
	v_mul_u32_u24_e32 v74, s10, v74
	v_mov_b32_e32 v75, 0
	v_cvt_pk_bf16_f32 v73, v68, v69
	v_mul_u32_u24_e32 v66, s10, v66
	v_mov_b32_e32 v67, 0
	v_cvt_pk_bf16_f32 v30, v30, v31
	v_cvt_pk_bf16_f32 v31, v32, v33
	v_cvt_pk_bf16_f32 v32, v26, v27
	v_add_u32_e32 v26, 0xa0, v148
	global_store_dwordx4 v[146:147], v[126:129], off
	v_cvt_pk_bf16_f32 v106, v118, v119
	v_cvt_pk_bf16_f32 v107, v120, v121
	v_cvt_pk_bf16_f32 v108, v114, v115
	v_cvt_pk_bf16_f32 v109, v116, v117
	global_store_dwordx4 v[110:111], v[94:97], off offset:256
	s_nop 1
	v_lshl_add_u64 v[94:95], v[90:91], 1, v[144:145]
	v_cvt_pk_bf16_f32 v49, v44, v45
	v_mul_u32_u24_e32 v42, s10, v42
	v_mov_b32_e32 v43, 0
	v_cvt_pk_bf16_f32 v14, v14, v15
	v_cvt_pk_bf16_f32 v15, v16, v17
	v_cvt_pk_bf16_f32 v16, v10, v11
	v_add_u32_e32 v10, 0xb0, v148
	global_store_dwordx4 v[110:111], v[106:109], off
	v_cvt_pk_bf16_f32 v90, v102, v103
	v_cvt_pk_bf16_f32 v91, v104, v105
	v_cvt_pk_bf16_f32 v92, v98, v99
	v_cvt_pk_bf16_f32 v93, v100, v101
	global_store_dwordx4 v[94:95], v[78:81], off offset:256
	v_cvt_pk_bf16_f32 v76, v82, v83
	v_cvt_pk_bf16_f32 v77, v84, v85
	v_lshl_add_u64 v[78:79], v[74:75], 1, v[144:145]
	v_cvt_pk_bf16_f32 v74, v86, v87
	v_cvt_pk_bf16_f32 v75, v88, v89
	v_lshl_add_u64 v[66:67], v[66:67], 1, v[144:145]
	v_cvt_pk_bf16_f32 v33, v28, v29
	v_mul_u32_u24_e32 v26, s10, v26
	v_mov_b32_e32 v27, 0
	global_store_dwordx4 v[94:95], v[90:93], off
	global_store_dwordx4 v[78:79], v[74:77], off
	global_store_dwordx4 v[78:79], v[70:73], off offset:256
	v_cvt_pk_bf16_f32 v62, v62, v63
	v_cvt_pk_bf16_f32 v63, v64, v65
	v_cvt_pk_bf16_f32 v64, v58, v59
	v_cvt_pk_bf16_f32 v65, v60, v61
	global_store_dwordx4 v[66:67], v[46:49], off offset:256
	s_nop 1
	v_cvt_pk_bf16_f32 v17, v12, v13
	v_lshl_add_u64 v[46:47], v[42:43], 1, v[144:145]
	v_mul_u32_u24_e32 v10, s10, v10
	v_mov_b32_e32 v11, 0
	global_store_dwordx4 v[66:67], v[62:65], off
	v_cvt_pk_bf16_f32 v42, v54, v55
	v_cvt_pk_bf16_f32 v43, v56, v57
	v_cvt_pk_bf16_f32 v44, v50, v51
	v_cvt_pk_bf16_f32 v45, v52, v53
	global_store_dwordx4 v[46:47], v[30:33], off offset:256
	s_nop 1
	global_store_dwordx4 v[46:47], v[42:45], off
	v_lshl_add_u64 v[30:31], v[26:27], 1, v[144:145]
	v_cvt_pk_bf16_f32 v26, v38, v39
	v_cvt_pk_bf16_f32 v27, v40, v41
	v_cvt_pk_bf16_f32 v28, v34, v35
	v_cvt_pk_bf16_f32 v29, v36, v37
	global_store_dwordx4 v[30:31], v[14:17], off offset:256
	v_cvt_pk_bf16_f32 v12, v18, v19
	v_cvt_pk_bf16_f32 v13, v20, v21
	v_lshl_add_u64 v[14:15], v[10:11], 1, v[144:145]
	v_cvt_pk_bf16_f32 v10, v22, v23
	v_cvt_pk_bf16_f32 v11, v24, v25
	v_cvt_pk_bf16_f32 v6, v6, v7
	v_cvt_pk_bf16_f32 v7, v8, v9
	v_cvt_pk_bf16_f32 v8, v2, v3
	v_cvt_pk_bf16_f32 v9, v4, v5
	s_and_b64 vcc, exec, s[36:37]
	s_mov_b32 s28, s6
	s_mov_b32 s78, s18
	s_mov_b64 s[10:11], s[38:39]
	s_mov_b64 s[40:41], s[20:21]
	global_store_dwordx4 v[30:31], v[26:29], off
	global_store_dwordx4 v[14:15], v[10:13], off
	global_store_dwordx4 v[14:15], v[6:9], off offset:256
	s_cbranch_vccnz .LBB0_97
